# ticket queue layout: split-K unit tickets before cost 40, finishing tickets before cost 16
# baseline (speedup 1.0000x reference)
.Lq_r2:
	s_cmpk_lt_u32 s14, 0xb2
	s_cbranch_scc0 .Lq_r3
	s_add_i32 s14, s14, -2
	s_branch .Lq_prompt
.Lq_r3:
	s_cmpk_lt_u32 s14, 0xba
	s_cbranch_scc0 .Lq_r4
	s_addk_i32 s14, 0xff4e
	s_lshl_b32 s10, s11, 3
	s_add_i32 s100, s14, s10
	s_branch .Lz_call
.Lq_r4:
	s_cmpk_lt_u32 s14, 0xea
	s_cbranch_scc0 .Lq_r5
	s_add_i32 s14, s14, -10
	s_branch .Lq_prompt
.Lq_r5:
	s_cmpk_lt_u32 s14, 0xf2
	s_cbranch_scc0 .Lq_r6
	s_addk_i32 s14, 0xff16
	s_lshl_b32 s10, s11, 3
	s_add_i32 s100, s14, s10
	s_branch .Lf_call
